# attention item start: q_norm weights loaded once per phase, rope table loads issued with the Q loads
# speedup vs baseline: 1.0083x; 1.0012x over previous
; #define LAS __attribute__((address_space(3)))
; DEVI int opaque_tid(int wv) { int ln; asm volatile("v_mbcnt_lo_u32_b32 %0, -1, 0\n\tv_mbcnt_hi_u32_b32 %0, -1, %0" : "=v"(ln)); return wv * 64 + ln; }
;     const int tid = opaque_tid(wv), lane = tid & 63, wave = wv, fr = lane & 15, fq = lane >> 4;
;     LAS unsigned char* Kl0 = (LAS unsigned char*)lds_raw;
;     const bf16_t* Z = (const bf16_t*)(p.ws + OFF_ZG); bf16_t* YB = (bf16_t*)(p.ws + OFF_YB);
;     const int nitems = 1024 + (l == 0 ? 128 : 0);
;     for (int it = blockIdx.x + it_lo; it < nitems; it += gridDim.x) {
;         int b, n, kvh, hp, qrow0; const bool isl = it < 1024;
;         if (isl) { b = it >> 6; n = (it >> 2) & 15; kvh = (it >> 1) & 1; hp = it & 1; qrow0 = b * 2048 + n * 128; }
;         else { const int i2 = it - 1024; b = i2 >> 3; n = (i2 >> 2) & 1; kvh = (i2 >> 1) & 1; hp = i2 & 1; qrow0 = NLAT + b * 256 + n * 128; }
;         const int hq0 = kvh * 4 + hp * 2;
;         const int ii = wave * 16 + fr;
;     ...
;                 const float* wp = p.in[12] + l * 64 + ks * 32 + fq * 8;
;                 const f32x4 w0 = *(const f32x4*)wp, w1 = *(const f32x4*)(wp + 4);
.LBB0_547:
	v_readlane_b32 s0, v253, 26
	v_readlane_b32 s1, v253, 27
	s_and_b64 s[0:1], s[0:1], exec
	s_movk_i32 s0, 0x480
	s_cselect_b32 s50, s0, 0x400
	v_readlane_b32 s0, v253, 12
	s_cmp_ge_i32 s0, s50
	v_mbcnt_lo_u32_b32 v0, -1, 0
	v_mbcnt_hi_u32_b32 v0, -1, v0
	s_cbranch_scc1 .LBB0_669
	v_readlane_b32 s0, v250, 8
	v_and_b32_e32 v3, 15, v0
	v_and_b32_e32 v2, 32, v0
	v_add_u32_e32 v4, s0, v0
	v_readlane_b32 s0, v252, 27
	v_cmp_lt_i32_e32 vcc, v228, v226
	v_readlane_b32 s2, v253, 31
	v_or_b32_e32 v149, s0, v3
	v_cmp_eq_u32_e64 s[0:1], 0, v2
	v_cndmask_b32_e32 v2, v225, v228, vcc
	v_cmp_lt_i32_e32 vcc, v227, v226
	v_lshlrev_b32_e32 v164, 2, v2
	v_ashrrev_i32_e32 v171, 3, v4
	v_cndmask_b32_e32 v2, v225, v227, vcc
	v_lshlrev_b32_e32 v165, 2, v2
	v_lshlrev_b32_e32 v2, 4, v0
	v_add_u32_e32 v4, 0x200, v4
	v_bfe_u32 v5, v0, 4, 2
	s_lshl_b32 s18, s2, 6
	s_lshl_b32 s51, s2, 3
	v_and_b32_e32 v2, 0x70, v2
	v_ashrrev_i32_e32 v172, 3, v4
	s_movk_i32 s2, 0x90
	v_and_b32_e32 v166, 16, v0
	v_lshlrev_b32_e32 v6, 3, v0
	v_add_u32_e32 v168, 0, v2
	v_lshlrev_b32_e32 v2, 2, v5
	v_bfe_u32 v0, v0, 2, 2
	v_mul_lo_u32 v173, v171, s2
	v_mul_lo_u32 v174, v172, s2
	s_lshl_b64 s[2:3], s[18:19], 2
	v_or_b32_e32 v0, v2, v0
	s_add_u32 s2, s84, s2
	v_and_b32_e32 v148, 56, v6
	v_mul_u32_u24_e32 v176, 0x90, v0
	s_addc_u32 s3, s85, s3
	v_lshlrev_b32_e32 v0, 5, v5
	v_cmp_eq_u32_e32 vcc, 0, v5
	v_lshlrev_b32_e32 v150, 4, v5
	v_lshl_add_u64 v[152:153], s[2:3], 0, v[0:1]
	v_mov_b32_e32 v151, v1
	v_lshlrev_b32_e32 v0, 1, v148
	v_cndmask_b32_e64 v167, 0, 1.0, vcc
	v_sub_u32_e32 v169, v2, v149
	v_and_b32_e32 v170, 24, v6
	v_mul_u32_u24_e32 v175, 0x90, v3
	v_lshl_add_u64 v[154:155], s[24:25], 0, v[150:151]
	v_lshl_add_u64 v[156:157], s[24:25], 0, v[0:1]
	v_lshlrev_b32_e32 v158, 1, v2
	v_readlane_b32 s52, v253, 12
	global_load_dwordx4 v[200:203], v[152:153], off
	global_load_dwordx4 v[204:207], v[152:153], off offset:16
	global_load_dwordx4 v[208:211], v[152:153], off offset:128
	global_load_dwordx4 v[212:215], v[152:153], off offset:144
	s_waitcnt vmcnt(0)
	s_branch .LBB0_550

; DEVI void unpack8(const u32x4 w, float (&v)[8]) { v[0] = bflo(w.x); v[1] = bfhi(w.x); v[2] = bflo(w.y); v[3] = bfhi(w.y); v[4] = bflo(w.z); v[5] = bfhi(w.z); v[6] = bflo(w.w); v[7] = bfhi(w.w); }
;     ...
;         bf16x8 Qf[2][2];
; #pragma unroll
;         for (int g = 0; g < 2; ++g)
; #pragma unroll
;             for (int ks = 0; ks < 2; ++ks) Qf[g][ks] = *(const bf16x8*)(Z + (size_t)(qrow0 + ii) * ZM + C_AQ + (hq0 + g) * 64 + ks * 32 + fq * 8);
;         {
;             const int qpos = (qrow0 + ii) & 2047; const bool up = (fq & 2) != 0;
;             float ssq[2]; float qv[2][2][8];
; #pragma unroll
;             for (int g = 0; g < 2; ++g) { ssq[g] = 0.f;
; #pragma unroll
;                 for (int ks = 0; ks < 2; ++ks) { unpack8(__builtin_bit_cast(u32x4, Qf[g][ks]), qv[g][ks]);
; #pragma unroll
;                     for (int e = 0; e < 8; ++e) ssq[g] += qv[g][ks][e] * qv[g][ks][e]; }
;                 ssq[g] += __shfl_xor(ssq[g], 16); ssq[g] += __shfl_xor(ssq[g], 32);
;                 ssq[g] = rsqrtf(ssq[g] * (1.0f / 64.0f) + EPS) * (0.125f * 1.4426950408889634f); }
; #pragma unroll
;             for (int ks = 0; ks < 2; ++ks) {
;                 const float* wp = p.in[12] + l * 64 + ks * 32 + fq * 8;
;                 const f32x4 w0 = *(const f32x4*)wp, w1 = *(const f32x4*)(wp + 4);
;                 const float* cp = (const float*)(p.ws + OFF_AT) + (size_t)((ks ? (qpos & 63) : (qpos >> 6)) * 16 + (fq & 1) * 8) * 2;
;                 f32x4 cs[4];
;                 if (isl) {
; #pragma unroll
;                     for (int q4 = 0; q4 < 4; ++q4) cs[q4] = *(const f32x4*)(cp + 4 * q4); }
.LBB0_554:
	s_bfe_u32 s12, s52, 0x10001
	s_lshl_b32 s3, s52, 1
	s_lshl_b32 s2, s12, 2
	s_and_b32 s3, s3, 2
	s_or_b32 s13, s2, s3
	v_add_u32_e32 v151, s4, v149
	v_mad_i64_i32 v[2:3], s[2:3], v151, s46, v[154:155]
	s_lshl_b32 s18, s13, 7
	v_lshl_add_u64 v[2:3], v[2:3], 0, s[18:19]
	global_load_dwordx4 v[20:23], v[2:3], off offset:3584
	s_waitcnt lgkmcnt(0)
	global_load_dwordx4 v[24:27], v[2:3], off offset:3648
	global_load_dwordx4 v[28:31], v[2:3], off offset:3712
	global_load_dwordx4 v[62:65], v[2:3], off offset:3776
	v_lshrrev_b32_e32 v216, 1, v151
	s_movk_i32 s4, 0x3e0
	v_and_or_b32 v216, v216, s4, v166
	v_readlane_b32 s4, v252, 19
	v_lshlrev_b32_e32 v216, 2, v216
	v_readlane_b32 s5, v252, 20
	s_nop 4
	global_load_dwordx4 v[4:7], v216, s[4:5] offset:48
	global_load_dwordx4 v[8:11], v216, s[4:5] offset:32
	global_load_dwordx4 v[12:15], v216, s[4:5] offset:16
	global_load_dwordx4 v[16:19], v216, s[4:5]
	v_cndmask_b32_e64 v0, 0, 1, s[6:7]
	v_cmp_ne_u32_e64 s[2:3], 1, v0
	s_andn2_b64 vcc, exec, s[6:7]
	s_waitcnt vmcnt(0)
	v_and_b32_e32 v59, 0xffff0000, v20
	v_lshlrev_b32_e32 v61, 16, v20
	v_and_b32_e32 v58, 0xffff0000, v28
	v_lshlrev_b32_e32 v60, 16, v28
	v_pk_mul_f32 v[2:3], v[58:59], v[58:59]
	v_lshlrev_b32_e32 v57, 16, v21
	v_lshlrev_b32_e32 v56, 16, v29
	v_pk_fma_f32 v[2:3], v[60:61], v[60:61], v[2:3]
	v_and_b32_e32 v55, 0xffff0000, v21
	v_and_b32_e32 v54, 0xffff0000, v29
	v_pk_fma_f32 v[2:3], v[56:57], v[56:57], v[2:3]
	v_lshlrev_b32_e32 v39, 16, v22
	v_lshlrev_b32_e32 v38, 16, v30
	v_pk_fma_f32 v[2:3], v[54:55], v[54:55], v[2:3]
	v_and_b32_e32 v37, 0xffff0000, v22
	v_and_b32_e32 v36, 0xffff0000, v30
	v_pk_fma_f32 v[2:3], v[38:39], v[38:39], v[2:3]
	v_and_b32_e32 v52, 0xffff0000, v24
	v_lshlrev_b32_e32 v53, 16, v24
	v_and_b32_e32 v44, 0xffff0000, v62
	v_lshlrev_b32_e32 v45, 16, v62
	v_lshlrev_b32_e32 v35, 16, v23
	v_lshlrev_b32_e32 v34, 16, v31
	v_pk_fma_f32 v[2:3], v[36:37], v[36:37], v[2:3]
	v_pk_mul_f32 v[66:67], v[52:53], v[52:53]
	v_pk_mul_f32 v[70:71], v[44:45], v[44:45]
	v_and_b32_e32 v33, 0xffff0000, v23
	v_and_b32_e32 v32, 0xffff0000, v31
	v_pk_fma_f32 v[2:3], v[34:35], v[34:35], v[2:3]
	v_and_b32_e32 v50, 0xffff0000, v25
	v_lshlrev_b32_e32 v51, 16, v25
	v_pk_fma_f32 v[2:3], v[32:33], v[32:33], v[2:3]
	v_mov_b32_e32 v20, v71
	v_mov_b32_e32 v21, v67
	v_and_b32_e32 v42, 0xffff0000, v63
	v_lshlrev_b32_e32 v43, 16, v63
	v_pk_mul_f32 v[24:25], v[50:51], v[50:51]
	v_pk_add_f32 v[20:21], v[20:21], v[2:3]
	v_pk_mul_f32 v[22:23], v[42:43], v[42:43]
	v_mov_b32_e32 v71, v66
	v_and_b32_e32 v48, 0xffff0000, v26
	v_lshlrev_b32_e32 v49, 16, v26
	v_and_b32_e32 v40, 0xffff0000, v64
	v_lshlrev_b32_e32 v41, 16, v64
	v_pk_add_f32 v[20:21], v[70:71], v[20:21]
	v_mov_b32_e32 v62, v23
	v_mov_b32_e32 v63, v25
	v_pk_mul_f32 v[68:69], v[48:49], v[48:49]
	v_pk_mul_f32 v[28:29], v[40:41], v[40:41]
	v_pk_add_f32 v[20:21], v[62:63], v[20:21]
	v_mov_b32_e32 v23, v24
	v_and_b32_e32 v46, 0xffff0000, v27
	v_lshlrev_b32_e32 v47, 16, v27
	v_and_b32_e32 v2, 0xffff0000, v65
	v_lshlrev_b32_e32 v3, 16, v65
	v_pk_add_f32 v[20:21], v[22:23], v[20:21]
	v_mov_b32_e32 v22, v29
	v_mov_b32_e32 v23, v69
	v_pk_mul_f32 v[26:27], v[46:47], v[46:47]
	v_pk_mul_f32 v[30:31], v[2:3], v[2:3]
	v_pk_add_f32 v[20:21], v[22:23], v[20:21]
	v_mov_b32_e32 v29, v68
	v_pk_add_f32 v[20:21], v[28:29], v[20:21]
	v_mov_b32_e32 v22, v31
	v_mov_b32_e32 v23, v27
	v_pk_add_f32 v[20:21], v[22:23], v[20:21]
	v_mov_b32_e32 v31, v26
	v_pk_add_f32 v[20:21], v[30:31], v[20:21]
	v_mov_b32_e32 v24, v204
	v_mov_b32_e32 v25, v205
	v_mov_b32_e32 v26, v206
	v_mov_b32_e32 v27, v207
	v_mov_b32_e32 v28, v200
	v_mov_b32_e32 v29, v201
	v_mov_b32_e32 v30, v202
	v_mov_b32_e32 v31, v203
	ds_bpermute_b32 v23, v164, v21
	ds_bpermute_b32 v22, v164, v20
	s_waitcnt lgkmcnt(0)
	v_pk_add_f32 v[20:21], v[20:21], v[22:23]
	ds_bpermute_b32 v23, v165, v21
	ds_bpermute_b32 v22, v165, v20
	s_cbranch_vccnz .LBB0_556
	v_lshrrev_b32_e32 v0, 1, v151
	s_movk_i32 s4, 0x3e0
	v_and_or_b32 v0, v0, s4, v166
	v_readlane_b32 s4, v252, 19
	v_lshlrev_b32_e32 v0, 2, v0
	v_readlane_b32 s5, v252, 20
	s_nop 4

; DEVI unsigned cvt_pk_bf16(float lo, float hi) { unsigned r; asm volatile("v_cvt_pk_bf16_f32 %0, %1, %2" : "=v"(r) : "v"(lo), "v"(hi)); return r; }
;     ...
;             for (int ks = 0; ks < 2; ++ks) {
;                 const float* wp = p.in[12] + l * 64 + ks * 32 + fq * 8;
;                 const f32x4 w0 = *(const f32x4*)wp, w1 = *(const f32x4*)(wp + 4);
;                 const float* cp = (const float*)(p.ws + OFF_AT) + (size_t)((ks ? (qpos & 63) : (qpos >> 6)) * 16 + (fq & 1) * 8) * 2;
;                 f32x4 cs[4];
;                 if (isl) {
; #pragma unroll
;                     for (int q4 = 0; q4 < 4; ++q4) cs[q4] = *(const f32x4*)(cp + 4 * q4); }
; #pragma unroll
;                 for (int g = 0; g < 2; ++g) {
; #pragma unroll
;                     for (int e = 0; e < 8; ++e) { float v = qv[g][ks][e] * ssq[g] * (e < 4 ? w0[e & 3] : w1[e & 3]);
;                         if (isl) { const float o = __shfl_xor(v, 32); const float cc = cs[e >> 1][(e & 1) * 2], sn = cs[e >> 1][(e & 1) * 2 + 1]; v = up ? o * sn + v * cc : v * cc - o * sn; }
;                         qv[g][ks][e] = v; }
;                     Qf[g][ks] = mk_frag(cvt_pk_bf16(qv[g][ks][0], qv[g][ks][1]), cvt_pk_bf16(qv[g][ks][2], qv[g][ks][3]), cvt_pk_bf16(qv[g][ks][4], qv[g][ks][5]), cvt_pk_bf16(qv[g][ks][6], qv[g][ks][7])); }
.LBB0_574:
	v_cvt_pk_bf16_f32 v24, v28, v29
	v_cvt_pk_bf16_f32 v25, v30, v31
	v_cvt_pk_bf16_f32 v26, v33, v35
	v_cvt_pk_bf16_f32 v27, v34, v27
	v_mov_b32_e32 v32, v212
	v_mov_b32_e32 v33, v213
	v_mov_b32_e32 v34, v214
	v_mov_b32_e32 v35, v215
	v_mov_b32_e32 v36, v208
	v_mov_b32_e32 v37, v209
	v_mov_b32_e32 v38, v210
	v_mov_b32_e32 v39, v211
	s_and_b64 vcc, exec, s[2:3]
	s_cbranch_vccz .LBB0_654
	v_mul_f32_e32 v28, v0, v53
	s_and_b64 vcc, exec, s[2:3]
	s_waitcnt vmcnt(0)
	v_mul_f32_e32 v28, v28, v36
	s_cbranch_vccz .LBB0_655
